# convT pipeline: wait counts stores too (vmcnt 5D instead of 4D, full 3-tile lookahead), dummy prologue loads keep the count uniform
# speedup vs baseline: 1.0003x; 1.0003x over previous
; DEVI void convT(const float* src, int K, int N, u16* dst, int Npad, int mode, const float* gk, float* tile, int first) {
;     ...
;     for (int ti = first; ti < ntk * ntn; ti += gridDim.x) {
;         const int k0 = (ti % ntk) * 64, n0 = (ti / ntk) * 64;
;         for (int i = tid; i < 1024; i += 512) { const int kk = i >> 4, n4 = (i & 15) * 4, n = n0 + n4;
;             f32x4 v = (f32x4){0.f, 0.f, 0.f, 0.f}; if (n < N) { v = *(const f32x4*)(src + (size_t)(k0 + kk) * N + n); if (gk) v = v * gk[k0 + kk]; }
;             float* tp = tile + kk * 65 + n4; tp[0] = v[0]; tp[1] = v[1]; tp[2] = v[2]; tp[3] = v[3]; }
.Lcv_ret0:
	v_cmp_gt_i32_e32 vcc, s63, v3
	v_add_u32_e32 v70, s64, v2
	s_nop 1
	v_cndmask_b32_e32 v70, 0, v70, vcc
	v_mad_u32_u24 v70, v1, s62, v70
	global_load_dwordx4 v[20:23], v70, s[60:61]
	s_lshl_b32 s2, s62, 5
	s_add_u32 s60, s60, s2
	s_addc_u32 s61, s61, 0
	global_load_dwordx4 v[24:27], v70, s[60:61]
	global_load_dword v28, v4, s[66:67]
	global_load_dword v29, v4, s[66:67] offset:128
	s_mov_b64 s[40:41], s[70:71]
	s_mov_b32 s42, s63
	s_mov_b32 s43, s68
	global_load_dword v64, v4, s[66:67]
	s_mul_i32 s38, 1, 248
	s_add_u32 s38, s38, s39
	s_mov_b32 s79, 1
	s_branch .Lcv_desc
.Lcv_ret1:
	v_cmp_gt_i32_e32 vcc, s63, v3
	v_add_u32_e32 v70, s64, v2
	s_nop 1
	v_cndmask_b32_e32 v70, 0, v70, vcc
	v_mad_u32_u24 v70, v1, s62, v70
	global_load_dwordx4 v[32:35], v70, s[60:61]
	s_lshl_b32 s2, s62, 5
	s_add_u32 s60, s60, s2
	s_addc_u32 s61, s61, 0
	global_load_dwordx4 v[36:39], v70, s[60:61]
	global_load_dword v40, v4, s[66:67]
	global_load_dword v41, v4, s[66:67] offset:128
	s_mov_b64 s[44:45], s[70:71]
	s_mov_b32 s50, s63
	s_mov_b32 s51, s68
	global_load_dword v64, v4, s[66:67]
	s_mul_i32 s38, 2, 248
	s_add_u32 s38, s38, s39
	s_mov_b32 s79, 2
	s_branch .Lcv_desc
.Lcv_ret2:
	v_cmp_gt_i32_e32 vcc, s63, v3
	v_add_u32_e32 v70, s64, v2
	s_nop 1
	v_cndmask_b32_e32 v70, 0, v70, vcc
	v_mad_u32_u24 v70, v1, s62, v70
	global_load_dwordx4 v[44:47], v70, s[60:61]
	s_lshl_b32 s2, s62, 5
	s_add_u32 s60, s60, s2
	s_addc_u32 s61, s61, 0
	global_load_dwordx4 v[48:51], v70, s[60:61]
	global_load_dword v52, v4, s[66:67]
	global_load_dword v53, v4, s[66:67] offset:128
	s_mov_b64 s[52:53], s[70:71]
	s_mov_b32 s54, s63
	s_mov_b32 s55, s68
	global_load_dword v64, v4, s[66:67]
	s_mov_b32 s36, 0

; DEVI void convT(const float* src, int K, int N, u16* dst, int Npad, int mode, const float* gk, float* tile, int first) {
;     ...
;     for (int ti = first; ti < ntk * ntn; ti += gridDim.x) {
;         const int k0 = (ti % ntk) * 64, n0 = (ti / ntk) * 64;
;         for (int i = tid; i < 1024; i += 512) { const int kk = i >> 4, n4 = (i & 15) * 4, n = n0 + n4;
;             f32x4 v = (f32x4){0.f, 0.f, 0.f, 0.f}; if (n < N) { v = *(const f32x4*)(src + (size_t)(k0 + kk) * N + n); if (gk) v = v * gk[k0 + kk]; }
;             float* tp = tile + kk * 65 + n4; tp[0] = v[0]; tp[1] = v[1]; tp[2] = v[2]; tp[3] = v[3]; }
.Lcv_ret3:
	v_cmp_gt_i32_e32 vcc, s63, v3
	v_add_u32_e32 v70, s64, v2
	s_nop 1
	v_cndmask_b32_e32 v70, 0, v70, vcc
	v_mad_u32_u24 v70, v1, s62, v70
	global_load_dwordx4 v[56:59], v70, s[60:61]
	s_lshl_b32 s2, s62, 5
	s_add_u32 s60, s60, s2
	s_addc_u32 s61, s61, 0
	global_load_dwordx4 v[60:63], v70, s[60:61]
	global_load_dword v64, v4, s[66:67]
	global_load_dword v65, v4, s[66:67] offset:128
	s_mov_b64 s[56:57], s[70:71]
	s_mov_b32 s58, s63
	s_mov_b32 s59, s68
	s_waitcnt vmcnt(15)
	s_bitcmp1_b32 s43, 2
	s_cbranch_scc0 .Lcv_nogk0
	v_mul_f32_e32 v20, v20, v28
	v_mul_f32_e32 v21, v21, v28
	v_mul_f32_e32 v22, v22, v28
	v_mul_f32_e32 v23, v23, v28
	v_mul_f32_e32 v24, v24, v29
	v_mul_f32_e32 v25, v25, v29
	v_mul_f32_e32 v26, v26, v29
	v_mul_f32_e32 v27, v27, v29

; DEVI void convT(const float* src, int K, int N, u16* dst, int Npad, int mode, const float* gk, float* tile, int first) {
;     ...
;     for (int ti = first; ti < ntk * ntn; ti += gridDim.x) {
;         const int k0 = (ti % ntk) * 64, n0 = (ti / ntk) * 64;
;         for (int i = tid; i < 1024; i += 512) { const int kk = i >> 4, n4 = (i & 15) * 4, n = n0 + n4;
;             f32x4 v = (f32x4){0.f, 0.f, 0.f, 0.f}; if (n < N) { v = *(const f32x4*)(src + (size_t)(k0 + kk) * N + n); if (gk) v = v * gk[k0 + kk]; }
;             float* tp = tile + kk * 65 + n4; tp[0] = v[0]; tp[1] = v[1]; tp[2] = v[2]; tp[3] = v[3]; }
.Lcv_ret4:
	v_cmp_gt_i32_e32 vcc, s63, v3
	v_add_u32_e32 v70, s64, v2
	s_nop 1
	v_cndmask_b32_e32 v70, 0, v70, vcc
	v_mad_u32_u24 v70, v1, s62, v70
	global_load_dwordx4 v[20:23], v70, s[60:61]
	s_lshl_b32 s2, s62, 5
	s_add_u32 s60, s60, s2
	s_addc_u32 s61, s61, 0
	global_load_dwordx4 v[24:27], v70, s[60:61]
	global_load_dword v28, v4, s[66:67]
	global_load_dword v29, v4, s[66:67] offset:128
	s_mov_b64 s[40:41], s[70:71]
	s_mov_b32 s42, s63
	s_mov_b32 s43, s68
	s_waitcnt vmcnt(15)
	s_bitcmp1_b32 s51, 2
	s_cbranch_scc0 .Lcv_nogk1
	v_mul_f32_e32 v32, v32, v40
	v_mul_f32_e32 v33, v33, v40
	v_mul_f32_e32 v34, v34, v40
	v_mul_f32_e32 v35, v35, v40
	v_mul_f32_e32 v36, v36, v41
	v_mul_f32_e32 v37, v37, v41
	v_mul_f32_e32 v38, v38, v41
	v_mul_f32_e32 v39, v39, v41

; DEVI void convT(const float* src, int K, int N, u16* dst, int Npad, int mode, const float* gk, float* tile, int first) {
;     ...
;     for (int ti = first; ti < ntk * ntn; ti += gridDim.x) {
;         const int k0 = (ti % ntk) * 64, n0 = (ti / ntk) * 64;
;         for (int i = tid; i < 1024; i += 512) { const int kk = i >> 4, n4 = (i & 15) * 4, n = n0 + n4;
;             f32x4 v = (f32x4){0.f, 0.f, 0.f, 0.f}; if (n < N) { v = *(const f32x4*)(src + (size_t)(k0 + kk) * N + n); if (gk) v = v * gk[k0 + kk]; }
;             float* tp = tile + kk * 65 + n4; tp[0] = v[0]; tp[1] = v[1]; tp[2] = v[2]; tp[3] = v[3]; }
.Lcv_ret5:
	v_cmp_gt_i32_e32 vcc, s63, v3
	v_add_u32_e32 v70, s64, v2
	s_nop 1
	v_cndmask_b32_e32 v70, 0, v70, vcc
	v_mad_u32_u24 v70, v1, s62, v70
	global_load_dwordx4 v[32:35], v70, s[60:61]
	s_lshl_b32 s2, s62, 5
	s_add_u32 s60, s60, s2
	s_addc_u32 s61, s61, 0
	global_load_dwordx4 v[36:39], v70, s[60:61]
	global_load_dword v40, v4, s[66:67]
	global_load_dword v41, v4, s[66:67] offset:128
	s_mov_b64 s[44:45], s[70:71]
	s_mov_b32 s50, s63
	s_mov_b32 s51, s68
	s_waitcnt vmcnt(15)
	s_bitcmp1_b32 s55, 2
	s_cbranch_scc0 .Lcv_nogk2
	v_mul_f32_e32 v44, v44, v52
	v_mul_f32_e32 v45, v45, v52
	v_mul_f32_e32 v46, v46, v52
	v_mul_f32_e32 v47, v47, v52
	v_mul_f32_e32 v48, v48, v53
	v_mul_f32_e32 v49, v49, v53
	v_mul_f32_e32 v50, v50, v53
	v_mul_f32_e32 v51, v51, v53

; DEVI void convT(const float* src, int K, int N, u16* dst, int Npad, int mode, const float* gk, float* tile, int first) {
;     ...
;     for (int ti = first; ti < ntk * ntn; ti += gridDim.x) {
;         const int k0 = (ti % ntk) * 64, n0 = (ti / ntk) * 64;
;         for (int i = tid; i < 1024; i += 512) { const int kk = i >> 4, n4 = (i & 15) * 4, n = n0 + n4;
;             f32x4 v = (f32x4){0.f, 0.f, 0.f, 0.f}; if (n < N) { v = *(const f32x4*)(src + (size_t)(k0 + kk) * N + n); if (gk) v = v * gk[k0 + kk]; }
;             float* tp = tile + kk * 65 + n4; tp[0] = v[0]; tp[1] = v[1]; tp[2] = v[2]; tp[3] = v[3]; }
.Lcv_ret6:
	v_cmp_gt_i32_e32 vcc, s63, v3
	v_add_u32_e32 v70, s64, v2
	s_nop 1
	v_cndmask_b32_e32 v70, 0, v70, vcc
	v_mad_u32_u24 v70, v1, s62, v70
	global_load_dwordx4 v[44:47], v70, s[60:61]
	s_lshl_b32 s2, s62, 5
	s_add_u32 s60, s60, s2
	s_addc_u32 s61, s61, 0
	global_load_dwordx4 v[48:51], v70, s[60:61]
	global_load_dword v52, v4, s[66:67]
	global_load_dword v53, v4, s[66:67] offset:128
	s_mov_b64 s[52:53], s[70:71]
	s_mov_b32 s54, s63
	s_mov_b32 s55, s68
	s_waitcnt vmcnt(15)
	s_bitcmp1_b32 s59, 2
	s_cbranch_scc0 .Lcv_nogk3
	v_mul_f32_e32 v56, v56, v64
	v_mul_f32_e32 v57, v57, v64
	v_mul_f32_e32 v58, v58, v64
	v_mul_f32_e32 v59, v59, v64
	v_mul_f32_e32 v60, v60, v65
	v_mul_f32_e32 v61, v61, v65
	v_mul_f32_e32 v62, v62, v65
	v_mul_f32_e32 v63, v63, v65
